# P5: half of each XCD's CUs start 35us late so epilogue store bursts interleave with other CUs' K-loops
# baseline (speedup 1.0000x reference)
; template <class Epi, bool HALO>
; __device__ __forceinline__ void gemm_phase(LAS unsigned char* lds, const bf16_t* Ag, const bf16_t* Btg, const int K, const int nM, const int nN, const int G, const int cidx, const int wave_, const Epi& E) {
;     int tid_ = fresh_tid(wave_); asm volatile("" : "+v"(tid_));
;     const int tid = tid_, wid = __builtin_amdgcn_readfirstlane(tid >> 6), lane = tid & 63, wr = wid >> 2, wc = wid & 3, fr = lane & 15, fq = lane >> 4;
;     const int nt = K / BK;
;     StaticOrder S; S.init(nM, nN, G, cidx);
;     unsigned voffA[2], voffB[2];
; #pragma unroll
;     for (int i = 0; i < 2; ++i) { int R, C; stage_rc(tid * 16 + i * 8192, R, C); const int Rb = (R & ~31) + perm32(R & 31);
;         const int Ra = HALO ? (R - 2 * (R >> 6)) : R;
;         voffA[i] = (unsigned)(Ra * K + C) * 2u; voffB[i] = (unsigned)(Rb * K + C) * 2u; }
;     const size_t kstep = (size_t)(BK * 2);
;     const size_t hstepB = (size_t)HALF * K * 2;
;     const size_t hstepA = HALO ? (size_t)124 * K * 2 : hstepB;
;     const unsigned ldsw = (unsigned)wid * 1024u;
;     const int aoff = lds_byte(wr * 64 + fr, fq * 8), boff = lds_byte(wc * 32 + fr, fq * 8);
;     ...
;     auto halo_row0 = [](int pm) -> long { int sb, t0, sl; halo_decode(pm, sb, t0, sl); return (long)sb + t0 - 1; };
;     Unit cur, nxt; int ui = 0;
;     if (!S.next(0, cur)) return;
;     f32x4 acc[2][2][4][2];
; #pragma unroll
;     for (int a = 0; a < 2; ++a)
; #pragma unroll
;         for (int b = 0; b < 2; ++b)
; #pragma unroll
;             for (int m = 0; m < 4; ++m)
; #pragma unroll
;                 for (int n = 0; n < 2; ++n) acc[a][b][m][n] = (f32x4){0.f, 0.f, 0.f, 0.f};
;     bf16x8 At[4][2], B0[2][2], B1[2][2];
;     const char* cA = PG8_ABASE(cur.pm); const char* cB = PG8_BBASE(cur.pn);
;     PG8_STAGE(PG8_SB(0, 0), cB, voffB); PG8_STAGE(PG8_SB(0, 1), cB + hstepB, voffB); PG8_STAGE(PG8_SA(0, 0), cA, voffA); PG8_STAGE(PG8_SA(0, 1), cA + hstepA, voffA);
;     if (wr == 1) PG8_BAR;
;     PG8_WAIT_V(2); PG8_BAR;
; __global__ void __launch_bounds__(NTHREADS, 2) hymba_fwd(Args args) {
;     ...
;             PHASE_ENV unsigned char* wl = ws + l * WS_WL;
;             pg8::EpiRes E{nullptr, nullptr, XN, l == 1 ? out : nullptr, l == 0 ? PS : nullptr};
;             pg8::gemm_phase<pg8::EpiRes, false>(ldsl, GB, (const bf16_t*)(wl + WO_DN), DFF, MT / 256, DM / 256, G, bx, wave, E);
.LBB0_866:
	s_or_b64 exec, exec, s[2:3]
	v_readlane_b32 s2, v254, 0
	v_readlane_b32 s3, v254, 1
	s_waitcnt lgkmcnt(0)
	v_mov_b32_e32 v0, v145
	s_barrier
	v_readlane_b32 s98, v254, 58
	s_bitcmp1_b32 s98, 3
	s_cbranch_scc0 STG5_skip
	s_memrealtime s[98:99]
	s_waitcnt lgkmcnt(0)
	s_mov_b32 s100, s98
STG5_spin:
	s_sleep 4
	s_memrealtime s[98:99]
	s_waitcnt lgkmcnt(0)
	s_sub_u32 s98, s98, s100
	s_cmp_lt_u32 s98, 3500
	s_cbranch_scc1 STG5_spin
STG5_skip:
	s_and_b64 vcc, exec, s[16:17]
	v_mbcnt_lo_u32_b32 v0, -1, v0
	v_mbcnt_hi_u32_b32 v0, -1, v0
	v_add_u32_e32 v16, s81, v0
	s_nop 0
	v_readfirstlane_b32 s10, v16
	s_cbranch_vccnz .LBB0_982
	v_lshlrev_b32_e32 v0, 4, v16
	v_add_u32_e32 v1, 0x2000, v0
	v_ashrrev_i32_e32 v2, 31, v1
	v_lshrrev_b32_e32 v2, 22, v2
	v_add_u32_e32 v2, v1, v2
	v_ashrrev_i32_e32 v8, 10, v2
	s_load_dwordx4 s[4:7], s[2:3], 0xd8
	v_mul_i32_i24_e32 v2, 0x400, v8
	v_sub_u32_e32 v1, v1, v2
	v_lshrrev_b32_e32 v2, 4, v1
	v_bitop3_b32 v1, v2, v1, 32 bitop3:0x6c
	v_ashrrev_i32_e32 v2, 31, v1
	s_waitcnt lgkmcnt(0)
	s_add_u32 s0, s6, 0xf400000
	v_lshrrev_b32_e32 v2, 26, v2
	s_addc_u32 s1, s7, 0
	v_readlane_b32 s2, v255, 6
	v_add_u32_e32 v2, v1, v2
	v_lshlrev_b32_e32 v3, 3, v8
	s_add_u32 s2, s6, s2
	v_ashrrev_i32_e32 v9, 6, v2
	v_and_b32_e32 v3, -16, v3
	s_addc_u32 s3, s7, 0
	v_add_u32_e32 v3, v9, v3
	s_add_u32 s30, s2, 0x1200000
	v_and_b32_e32 v4, 3, v9
	s_mov_b32 s2, 0xffffe0
	v_lshrrev_b32_e32 v5, 2, v3
	v_lshlrev_b32_e32 v6, 1, v3
	v_and_b32_e32 v2, 0xc0, v2
	v_and_or_b32 v4, v3, s2, v4
	v_and_b32_e32 v5, 4, v5
	v_and_b32_e32 v6, 24, v6
	v_sub_u32_e32 v1, v1, v2
	v_or3_b32 v4, v4, v5, v6
	v_lshlrev_b32_e32 v5, 5, v8
	v_ashrrev_i16_sdwa v1, v184, sext(v1) dst_sel:DWORD dst_unused:UNUSED_PAD src0_sel:DWORD src1_sel:BYTE_0
	s_addc_u32 s31, s3, 0
	v_and_b32_e32 v10, 32, v5
	v_bfe_i32 v11, v1, 0, 16
	s_movk_i32 s3, 0xb00
	v_mul_u32_u24_e32 v4, 0xb00, v4
	v_add_u32_e32 v1, v10, v11
	v_mul_lo_u32 v2, v3, s3
	v_add_lshl_u32 v128, v4, v1, 1
	v_add_lshl_u32 v130, v1, v2, 1
	v_bfe_i32 v1, v16, 27, 1
	v_lshrrev_b32_e32 v1, 22, v1
	v_add_u32_e32 v1, v0, v1
	v_and_b32_e32 v1, 0xfffffc00, v1
	v_sub_u32_e32 v0, v0, v1
	v_lshrrev_b32_e32 v1, 4, v0
	v_ashrrev_i32_e32 v2, 31, v16
	v_bitop3_b32 v0, v1, v0, 32 bitop3:0x6c
	v_lshrrev_b32_e32 v2, 26, v2
	v_ashrrev_i32_e32 v1, 31, v0
	v_add_u32_e32 v2, v16, v2
	v_lshrrev_b32_e32 v1, 26, v1
	v_ashrrev_i32_e32 v13, 6, v2
	v_add_u32_e32 v1, v0, v1
	v_lshlrev_b32_e32 v2, 3, v13
	v_ashrrev_i32_e32 v12, 6, v1
	v_and_b32_e32 v2, -16, v2
	v_add_u32_e32 v2, v12, v2
	v_and_b32_e32 v3, 3, v12
	v_lshrrev_b32_e32 v4, 2, v2
	v_lshlrev_b32_e32 v5, 1, v2
	v_and_b32_e32 v1, 0xc0, v1
	s_ashr_i32 s18, s10, 6
	v_and_or_b32 v3, v2, s2, v3
	v_and_b32_e32 v4, 4, v4
	v_and_b32_e32 v5, 24, v5
	v_sub_u32_e32 v0, v0, v1
	v_mul_lo_u32 v1, v2, s3
	v_readlane_b32 s3, v254, 16
	s_ashr_i32 s11, s10, 8
	s_lshl_b32 s33, s18, 10
	v_or3_b32 v3, v3, v4, v5
	v_lshlrev_b32_e32 v4, 5, v13
	v_ashrrev_i16_sdwa v0, v184, sext(v0) dst_sel:DWORD dst_unused:UNUSED_PAD src0_sel:DWORD src1_sel:BYTE_0
	s_mul_i32 s2, s3, 0x160000
	v_and_b32_e32 v14, 32, v4
	v_bfe_i32 v15, v0, 0, 16
	s_add_u32 s26, s30, s2
	s_mul_hi_i32 s2, s3, 0x160000
	v_mul_u32_u24_e32 v3, 0xb00, v3
	v_add_u32_e32 v0, v14, v15
	s_addc_u32 s27, s31, s2
	s_add_i32 s34, s33, 0
	v_add_lshl_u32 v144, v3, v0, 1
	s_add_i32 m0, s34, 0x10000
	v_add_lshl_u32 v132, v0, v1, 1
	global_load_lds_dwordx4 v144, s[26:27]
	s_add_i32 m0, s34, 0x12000
	s_add_u32 s2, s26, 0xb0000
	global_load_lds_dwordx4 v128, s[26:27]
	s_addc_u32 s3, s27, 0
	s_add_i32 m0, s34, 0x14000
	v_mov_b32_e32 v129, v145
	global_load_lds_dwordx4 v144, s[2:3]
	s_add_i32 m0, s34, 0x16000
	v_mov_b32_e32 v133, v145
	global_load_lds_dwordx4 v128, s[2:3]
	v_readlane_b32 s2, v254, 22
	s_mov_b32 s12, s2
	s_mul_i32 s2, s2, 0x160000
	s_add_u32 s8, s0, s2
	s_mul_hi_i32 s2, s12, 0x160000
	s_addc_u32 s9, s1, s2
	s_add_i32 s35, s34, 0x2000
	v_readlane_b32 s3, v254, 23
	s_mov_b32 m0, s34
	s_add_u32 s2, s8, 0xb0000
	global_load_lds_dwordx4 v132, s[8:9]
	s_mov_b32 m0, s35
	s_addc_u32 s3, s9, 0
	s_add_i32 s36, s34, 0x4000
	global_load_lds_dwordx4 v130, s[8:9]
	s_mov_b32 m0, s36
	s_add_i32 s37, s34, 0x6000
	global_load_lds_dwordx4 v132, s[2:3]
	s_mov_b32 m0, s37
	v_mov_b32_e32 v131, v145
	global_load_lds_dwordx4 v130, s[2:3]
	s_cmp_eq_u32 s11, 1
	v_lshl_add_u64 v[6:7], s[26:27], 0, v[144:145]
	v_lshl_add_u64 v[4:5], s[26:27], 0, v[128:129]
	v_lshl_add_u64 v[0:1], s[8:9], 0, v[132:133]
	s_cselect_b64 s[2:3], -1, 0
	s_cmp_lg_u32 s11, 1
	v_lshl_add_u64 v[2:3], s[8:9], 0, v[130:131]
	s_cbranch_scc1 .LBB0_869
	s_barrier
